# attention tile loops: half-wave max exchange via v_permlane32_swap instead of ds_bpermute; short causal-mask path for key tiles >= 2 (strategy 7, instruction selection)
# baseline (speedup 1.0000x reference)
.LBB0_372:
	s_mul_i32 s23, s79, 0x4400
	v_add_u32_e32 v88, s23, v187
	ds_read_b128 v[80:83], v88
	ds_read_b128 v[152:155], v88 offset:32
	ds_read_b128 v[168:171], v88 offset:64
	ds_read_b128 v[172:175], v88 offset:96
	ds_read_b128 v[84:87], v88 offset:8704
	ds_read_b128 v[200:203], v88 offset:8736
	ds_read_b128 v[204:207], v88 offset:8768
	ds_read_b128 v[216:219], v88 offset:8800
	s_waitcnt lgkmcnt(0)
	s_add_i32 s82, s78, s77
	s_waitcnt lgkmcnt(7)
	v_mfma_f32_32x32x16_bf16 v[96:111], v[80:83], v[112:115], 0
	s_cmp_ge_u32 s22, s66
	s_cselect_b64 s[42:43], -1, 0
	s_cmp_lt_u32 s22, 2
	s_cselect_b64 s[22:23], -1, 0
	s_or_b64 s[22:23], s[22:23], s[42:43]
	s_andn2_b64 vcc, exec, s[22:23]
	s_waitcnt lgkmcnt(3)
	v_mfma_f32_32x32x16_bf16 v[80:95], v[84:87], v[112:115], 0
	v_mfma_f32_32x32x16_bf16 v[96:111], v[152:155], v[116:119], v[96:111]
	s_waitcnt lgkmcnt(2)
	v_mfma_f32_32x32x16_bf16 v[80:95], v[200:203], v[116:119], v[80:95]
	v_mfma_f32_32x32x16_bf16 v[96:111], v[168:171], v[120:123], v[96:111]
	s_waitcnt lgkmcnt(1)
	v_mfma_f32_32x32x16_bf16 v[80:95], v[204:207], v[120:123], v[80:95]
	v_mfma_f32_32x32x16_bf16 v[96:111], v[172:175], v[124:127], v[96:111]
	s_waitcnt lgkmcnt(0)
	v_mfma_f32_32x32x16_bf16 v[80:95], v[216:219], v[124:127], v[80:95]
	s_nop 9
	v_mul_f32_e64 v168, v102, s24
	v_mul_f32_e64 v169, v103, s24
	v_mul_f32_e64 v102, v104, s24
	v_mul_f32_e64 v103, v105, s24
	v_mul_f32_e64 v172, v96, s24
	v_mul_f32_e64 v173, v97, s24
	v_pk_mul_f32 v[174:175], v[98:99], s[24:25] op_sel_hi:[1,0]
	v_pk_mul_f32 v[170:171], v[100:101], s[24:25] op_sel_hi:[1,0]
	v_pk_mul_f32 v[100:101], v[106:107], s[24:25] op_sel_hi:[1,0]
	v_pk_mul_f32 v[98:99], v[108:109], s[24:25] op_sel_hi:[1,0]
	v_mul_f32_e32 v105, 0x3e38aa3b, v80
	v_pk_mul_f32 v[96:97], v[110:111], s[24:25] op_sel_hi:[1,0]
	v_mul_f32_e32 v80, 0x3e38aa3b, v81
	v_mul_f32_e32 v81, 0x3e38aa3b, v82
	v_mul_f32_e32 v82, 0x3e38aa3b, v83
	v_mul_f32_e32 v83, 0x3e38aa3b, v84
	v_mul_f32_e32 v84, 0x3e38aa3b, v85
	v_mul_f32_e32 v85, 0x3e38aa3b, v86
	v_mul_f32_e32 v86, 0x3e38aa3b, v87
	v_mul_f32_e32 v87, 0x3e38aa3b, v88
	v_mul_f32_e32 v88, 0x3e38aa3b, v89
	v_mul_f32_e32 v89, 0x3e38aa3b, v90
	v_mul_f32_e32 v90, 0x3e38aa3b, v91
	v_mul_f32_e32 v91, 0x3e38aa3b, v92
	v_mul_f32_e32 v92, 0x3e38aa3b, v93
	v_mul_f32_e32 v93, 0x3e38aa3b, v94
	v_mul_f32_e32 v94, 0x3e38aa3b, v95
	s_cbranch_vccnz .LBB0_374
	s_cmpk_lt_u32 s77, 0x80
	s_cbranch_scc1 .Lat_genmask_a
	v_add_u32_e32 v95, s77, v188
	v_sub_u32_e32 v95, v158, v95
	v_cmp_le_i32_e32 vcc, 0, v95
	v_cmp_le_i32_e64 s[42:43], 1, v95
	v_cmp_le_i32_e64 s[44:45], 2, v95
	v_cndmask_b32_e32 v172, v214, v172, vcc
	v_cmp_le_i32_e32 vcc, 3, v95
	v_cndmask_b32_e64 v173, v214, v173, s[42:43]
	v_cmp_le_i32_e64 s[42:43], 8, v95
	v_cndmask_b32_e64 v174, v214, v174, s[44:45]
	v_cmp_le_i32_e64 s[44:45], 9, v95
	v_cndmask_b32_e32 v175, v214, v175, vcc
	v_cmp_le_i32_e32 vcc, 10, v95
	v_cndmask_b32_e64 v170, v214, v170, s[42:43]
	v_cmp_le_i32_e64 s[42:43], 11, v95
	v_cndmask_b32_e64 v171, v214, v171, s[44:45]
	v_cmp_le_i32_e64 s[44:45], 16, v95
	v_cndmask_b32_e32 v168, v214, v168, vcc
	v_cmp_le_i32_e32 vcc, 17, v95
	v_cndmask_b32_e64 v169, v214, v169, s[42:43]
	v_cmp_le_i32_e64 s[42:43], 18, v95
	v_cndmask_b32_e64 v102, v214, v102, s[44:45]
	v_cmp_le_i32_e64 s[44:45], 19, v95
	v_cndmask_b32_e32 v103, v214, v103, vcc
	v_cmp_le_i32_e32 vcc, 24, v95
	v_cndmask_b32_e64 v100, v214, v100, s[42:43]
	v_cmp_le_i32_e64 s[42:43], 25, v95
	v_cndmask_b32_e64 v101, v214, v101, s[44:45]
	v_cmp_le_i32_e64 s[44:45], 26, v95
	v_cndmask_b32_e32 v98, v214, v98, vcc
	v_cmp_le_i32_e32 vcc, 27, v95
	v_cndmask_b32_e64 v99, v214, v99, s[42:43]
	v_cmp_le_i32_e64 s[42:43], 32, v95
	v_cndmask_b32_e64 v96, v214, v96, s[44:45]
	v_cmp_le_i32_e64 s[44:45], 33, v95
	v_cndmask_b32_e32 v97, v214, v97, vcc
	v_cmp_le_i32_e32 vcc, 34, v95
	v_cndmask_b32_e64 v105, v214, v105, s[42:43]
	v_cmp_le_i32_e64 s[42:43], 35, v95
	v_cndmask_b32_e64 v80, v214, v80, s[44:45]
	v_cmp_le_i32_e64 s[44:45], 40, v95
	v_cndmask_b32_e32 v81, v214, v81, vcc
	v_cmp_le_i32_e32 vcc, 41, v95
	v_cndmask_b32_e64 v82, v214, v82, s[42:43]
	v_cmp_le_i32_e64 s[42:43], 42, v95
	v_cndmask_b32_e64 v83, v214, v83, s[44:45]
	v_cmp_le_i32_e64 s[44:45], 43, v95
	v_cndmask_b32_e32 v84, v214, v84, vcc
	v_cmp_le_i32_e32 vcc, 48, v95
	v_cndmask_b32_e64 v85, v214, v85, s[42:43]
	v_cmp_le_i32_e64 s[42:43], 49, v95
	v_cndmask_b32_e64 v86, v214, v86, s[44:45]
	v_cmp_le_i32_e64 s[44:45], 50, v95
	v_cndmask_b32_e32 v87, v214, v87, vcc
	v_cmp_le_i32_e32 vcc, 51, v95
	v_cndmask_b32_e64 v88, v214, v88, s[42:43]
	v_cmp_le_i32_e64 s[42:43], 56, v95
	v_cndmask_b32_e64 v89, v214, v89, s[44:45]
	v_cmp_le_i32_e64 s[44:45], 57, v95
	v_cndmask_b32_e32 v90, v214, v90, vcc
	v_cmp_le_i32_e32 vcc, 58, v95
	v_cndmask_b32_e64 v91, v214, v91, s[42:43]
	v_cmp_le_i32_e64 s[42:43], 59, v95
	v_cndmask_b32_e64 v92, v214, v92, s[44:45]
	v_cndmask_b32_e32 v93, v214, v93, vcc
	v_cndmask_b32_e64 v94, v214, v94, s[42:43]
	s_branch .LBB0_374
.Lat_genmask_a:
	s_cmpk_gt_u32 s82, 0x6f
	v_add_u32_e32 v95, s77, v188
	s_cselect_b64 s[22:23], -1, 0
	v_cmp_eq_u32_e32 vcc, s77, v198
	s_or_b64 s[42:43], s[22:23], vcc
	v_cmp_le_u32_e32 vcc, v95, v158
	v_add_u32_e32 v104, s77, v197
	s_and_b64 vcc, vcc, s[42:43]
	v_cmp_eq_u32_e64 s[42:43], 0, v104
	v_cndmask_b32_e32 v172, v214, v172, vcc
	v_cmp_lt_u32_e32 vcc, v95, v158
	s_or_b64 s[42:43], s[22:23], s[42:43]
	v_add_u32_e32 v104, s77, v196
	s_and_b64 vcc, vcc, s[42:43]
	v_add_u32_e32 v106, 2, v95
	v_cmp_eq_u32_e64 s[42:43], 0, v104
	v_cndmask_b32_e32 v173, v214, v173, vcc
	v_cmp_le_u32_e32 vcc, v106, v158
	s_or_b64 s[42:43], s[22:23], s[42:43]
	v_add_u32_e32 v104, s77, v195
	s_and_b64 vcc, vcc, s[42:43]
	v_add_u32_e32 v106, 3, v95
	v_cmp_eq_u32_e64 s[42:43], 0, v104
	v_cndmask_b32_e32 v174, v214, v174, vcc
	v_cmp_le_u32_e32 vcc, v106, v158
	s_or_b64 s[42:43], s[22:23], s[42:43]
	v_add_u32_e32 v104, s77, v194
	s_and_b64 vcc, vcc, s[42:43]
	v_add_u32_e32 v106, 8, v95
	v_cmp_eq_u32_e64 s[42:43], 0, v104
	v_cndmask_b32_e32 v175, v214, v175, vcc
	v_cmp_le_u32_e32 vcc, v106, v158
	s_or_b64 s[42:43], s[22:23], s[42:43]
	v_add_u32_e32 v104, s77, v193
	s_and_b64 vcc, vcc, s[42:43]
	v_add_u32_e32 v106, 9, v95
	v_cmp_eq_u32_e64 s[42:43], 0, v104
	v_cndmask_b32_e32 v170, v214, v170, vcc
	v_cmp_le_u32_e32 vcc, v106, v158
	s_or_b64 s[42:43], s[22:23], s[42:43]
	v_add_u32_e32 v104, s77, v192
	s_and_b64 vcc, vcc, s[42:43]
	v_add_u32_e32 v106, 10, v95
	v_cmp_eq_u32_e64 s[42:43], 0, v104
	v_cndmask_b32_e32 v171, v214, v171, vcc
	v_cmp_le_u32_e32 vcc, v106, v158
	s_or_b64 s[42:43], s[22:23], s[42:43]
	v_add_u32_e32 v104, s77, v191
	s_and_b64 vcc, vcc, s[42:43]
	v_add_u32_e32 v106, 11, v95
	v_cmp_eq_u32_e64 s[42:43], 0, v104
	v_cndmask_b32_e32 v168, v214, v168, vcc
	v_cmp_le_u32_e32 vcc, v106, v158
	s_or_b64 s[22:23], s[22:23], s[42:43]
	v_or_b32_e32 v106, 16, v95
	s_and_b64 vcc, vcc, s[22:23]
	v_or_b32_e32 v104, 17, v95
	v_cmp_lt_u32_e64 s[48:49], s11, v106
	v_cmp_eq_u32_e64 s[52:53], v106, v158
	v_cndmask_b32_e32 v169, v214, v169, vcc
	v_cmp_le_u32_e32 vcc, v106, v158
	v_cmp_lt_u32_e64 s[44:45], s11, v104
	v_cmp_eq_u32_e64 s[50:51], v104, v149
	s_or_b64 s[22:23], s[48:49], s[52:53]
	v_cmp_le_u32_e64 s[42:43], v104, v149
	s_or_b64 s[44:45], s[44:45], s[50:51]
	s_and_b64 vcc, vcc, s[22:23]
	v_or_b32_e32 v106, 18, v95
	v_cndmask_b32_e32 v102, v214, v102, vcc
	s_and_b64 vcc, s[42:43], s[44:45]
	v_or_b32_e32 v104, 19, v95
	v_cmp_lt_u32_e64 s[48:49], s11, v106
	v_cmp_eq_u32_e64 s[52:53], v106, v158
	v_cndmask_b32_e32 v103, v214, v103, vcc
	v_cmp_le_u32_e32 vcc, v106, v158
	v_cmp_lt_u32_e64 s[44:45], s11, v104
	v_cmp_eq_u32_e64 s[50:51], v104, v149
	s_or_b64 s[22:23], s[48:49], s[52:53]
	v_cmp_le_u32_e64 s[42:43], v104, v149
	s_or_b64 s[44:45], s[44:45], s[50:51]
	s_and_b64 vcc, vcc, s[22:23]
	v_or_b32_e32 v106, 24, v95
	v_cndmask_b32_e32 v100, v214, v100, vcc
	s_and_b64 vcc, s[42:43], s[44:45]
	v_or_b32_e32 v104, 25, v95
	v_cmp_lt_u32_e64 s[48:49], s11, v106
	v_cmp_eq_u32_e64 s[52:53], v106, v158
	v_cndmask_b32_e32 v101, v214, v101, vcc
	v_cmp_le_u32_e32 vcc, v106, v158
	v_cmp_lt_u32_e64 s[44:45], s11, v104
	v_cmp_eq_u32_e64 s[50:51], v104, v149
	s_or_b64 s[22:23], s[48:49], s[52:53]
	v_cmp_le_u32_e64 s[42:43], v104, v149
	s_or_b64 s[44:45], s[44:45], s[50:51]
	s_and_b64 vcc, vcc, s[22:23]
	v_or_b32_e32 v106, 26, v95
	v_cndmask_b32_e32 v98, v214, v98, vcc
	s_and_b64 vcc, s[42:43], s[44:45]
	v_or_b32_e32 v104, 27, v95
	v_cmp_lt_u32_e64 s[48:49], s11, v106
	v_cmp_eq_u32_e64 s[52:53], v106, v158
	v_cndmask_b32_e32 v99, v214, v99, vcc
	v_cmp_le_u32_e32 vcc, v106, v158
	v_cmp_lt_u32_e64 s[44:45], s11, v104
	v_cmp_eq_u32_e64 s[50:51], v104, v149
	s_or_b64 s[22:23], s[48:49], s[52:53]
	v_cmp_le_u32_e64 s[42:43], v104, v149
	s_or_b64 s[44:45], s[44:45], s[50:51]
	s_and_b64 vcc, vcc, s[22:23]
	v_cndmask_b32_e32 v96, v214, v96, vcc
	s_and_b64 vcc, s[42:43], s[44:45]
	v_add_u32_e32 v104, s77, v190
	v_add_u32_e32 v106, 32, v95
	v_cndmask_b32_e32 v97, v214, v97, vcc
	v_cmp_lt_u32_e32 vcc, s11, v106
	v_cmp_eq_u32_e64 s[42:43], 0, v104
	s_or_b64 s[22:23], vcc, s[42:43]
	v_cmp_le_u32_e32 vcc, v106, v158
	v_or_b32_e32 v106, 33, v95
	s_and_b64 vcc, vcc, s[22:23]
	v_or_b32_e32 v104, 34, v95
	v_cmp_lt_u32_e64 s[48:49], s11, v106
	v_cmp_eq_u32_e64 s[52:53], v106, v158
	v_cndmask_b32_e32 v105, v214, v105, vcc
	v_cmp_le_u32_e32 vcc, v106, v158
	v_cmp_lt_u32_e64 s[44:45], s11, v104
	v_cmp_eq_u32_e64 s[50:51], v104, v149
	s_or_b64 s[22:23], s[48:49], s[52:53]
	v_cmp_le_u32_e64 s[42:43], v104, v149
	s_or_b64 s[44:45], s[44:45], s[50:51]
	s_and_b64 vcc, vcc, s[22:23]
	v_or_b32_e32 v106, 35, v95
	v_cndmask_b32_e32 v80, v214, v80, vcc
	s_and_b64 vcc, s[42:43], s[44:45]
	v_or_b32_e32 v104, 40, v95
	v_cmp_lt_u32_e64 s[48:49], s11, v106
	v_cmp_eq_u32_e64 s[52:53], v106, v158
	v_cndmask_b32_e32 v81, v214, v81, vcc
	v_cmp_le_u32_e32 vcc, v106, v158
	v_cmp_lt_u32_e64 s[44:45], s11, v104
	v_cmp_eq_u32_e64 s[50:51], v104, v149
	s_or_b64 s[22:23], s[48:49], s[52:53]
	v_cmp_le_u32_e64 s[42:43], v104, v149
	s_or_b64 s[44:45], s[44:45], s[50:51]
	s_and_b64 vcc, vcc, s[22:23]
	v_or_b32_e32 v106, 41, v95
	v_cndmask_b32_e32 v82, v214, v82, vcc
	s_and_b64 vcc, s[42:43], s[44:45]
	v_or_b32_e32 v104, 42, v95
	v_cmp_lt_u32_e64 s[48:49], s11, v106
	v_cmp_eq_u32_e64 s[52:53], v106, v158
	v_cndmask_b32_e32 v83, v214, v83, vcc
	v_cmp_le_u32_e32 vcc, v106, v158
	v_cmp_lt_u32_e64 s[44:45], s11, v104
	v_cmp_eq_u32_e64 s[50:51], v104, v149
	s_or_b64 s[22:23], s[48:49], s[52:53]
	v_cmp_le_u32_e64 s[42:43], v104, v149
	s_or_b64 s[44:45], s[44:45], s[50:51]
	s_and_b64 vcc, vcc, s[22:23]
	v_or_b32_e32 v106, 43, v95
	v_cndmask_b32_e32 v84, v214, v84, vcc
	s_and_b64 vcc, s[42:43], s[44:45]
	v_or_b32_e32 v104, 48, v95
	v_cmp_lt_u32_e64 s[48:49], s11, v106
	v_cmp_eq_u32_e64 s[52:53], v106, v158
	v_cndmask_b32_e32 v85, v214, v85, vcc
	v_cmp_le_u32_e32 vcc, v106, v158
	v_cmp_lt_u32_e64 s[44:45], s11, v104
	v_cmp_eq_u32_e64 s[50:51], v104, v149
	s_or_b64 s[22:23], s[48:49], s[52:53]
	v_cmp_le_u32_e64 s[42:43], v104, v149
	s_or_b64 s[44:45], s[44:45], s[50:51]
	s_and_b64 vcc, vcc, s[22:23]
	v_or_b32_e32 v106, 49, v95
	v_cndmask_b32_e32 v86, v214, v86, vcc
	s_and_b64 vcc, s[42:43], s[44:45]
	v_or_b32_e32 v104, 50, v95
	v_cmp_lt_u32_e64 s[48:49], s11, v106
	v_cmp_eq_u32_e64 s[52:53], v106, v158
	v_cndmask_b32_e32 v87, v214, v87, vcc
	v_cmp_le_u32_e32 vcc, v106, v158
	v_cmp_lt_u32_e64 s[44:45], s11, v104
	v_cmp_eq_u32_e64 s[50:51], v104, v149
	s_or_b64 s[22:23], s[48:49], s[52:53]
	v_cmp_le_u32_e64 s[42:43], v104, v149
	s_or_b64 s[44:45], s[44:45], s[50:51]
	s_and_b64 vcc, vcc, s[22:23]
	v_or_b32_e32 v106, 51, v95
	v_cndmask_b32_e32 v88, v214, v88, vcc
	s_and_b64 vcc, s[42:43], s[44:45]
	v_or_b32_e32 v104, 56, v95
	v_cmp_lt_u32_e64 s[48:49], s11, v106
	v_cmp_eq_u32_e64 s[52:53], v106, v158
	v_cndmask_b32_e32 v89, v214, v89, vcc
	v_cmp_le_u32_e32 vcc, v106, v158
	v_cmp_lt_u32_e64 s[44:45], s11, v104
	v_cmp_eq_u32_e64 s[50:51], v104, v149
	s_or_b64 s[22:23], s[48:49], s[52:53]
	v_cmp_le_u32_e64 s[42:43], v104, v149
	s_or_b64 s[44:45], s[44:45], s[50:51]
	s_and_b64 vcc, vcc, s[22:23]
	v_or_b32_e32 v106, 57, v95
	v_cndmask_b32_e32 v90, v214, v90, vcc
	s_and_b64 vcc, s[42:43], s[44:45]
	v_or_b32_e32 v104, 58, v95
	v_cmp_lt_u32_e64 s[48:49], s11, v106
	v_cmp_eq_u32_e64 s[52:53], v106, v158
	v_cndmask_b32_e32 v91, v214, v91, vcc
	v_cmp_le_u32_e32 vcc, v106, v158
	v_cmp_lt_u32_e64 s[44:45], s11, v104
	v_cmp_eq_u32_e64 s[50:51], v104, v149
	s_or_b64 s[22:23], s[48:49], s[52:53]
	v_cmp_le_u32_e64 s[42:43], v104, v149
	s_or_b64 s[44:45], s[44:45], s[50:51]
	s_and_b64 vcc, vcc, s[22:23]
	v_add_u32_e32 v104, s77, v189
	v_add_u32_e32 v95, 59, v95
	v_cndmask_b32_e32 v92, v214, v92, vcc
	s_and_b64 vcc, s[42:43], s[44:45]
	v_cmp_lt_u32_e64 s[42:43], s11, v95
	v_cmp_eq_u32_e64 s[44:45], 0, v104
	v_cndmask_b32_e32 v93, v214, v93, vcc
	v_cmp_le_u32_e32 vcc, v95, v158
	s_or_b64 s[22:23], s[42:43], s[44:45]
	s_and_b64 vcc, vcc, s[22:23]
	v_cndmask_b32_e32 v94, v214, v94, vcc
.LBB0_374:
	s_mov_b32 s22, 0xff800000
	v_max3_f32 v95, v172, s22, v173
	v_max3_f32 v95, v95, v174, v175
	v_max3_f32 v95, v95, v170, v171
	v_max3_f32 v95, v95, v168, v169
	v_max3_f32 v95, v95, v102, v103
	v_max3_f32 v95, v95, v100, v101
	v_max3_f32 v95, v95, v98, v99
	v_max3_f32 v95, v95, v96, v97
	v_max3_f32 v95, v95, v105, v80
	v_max3_f32 v95, v95, v81, v82
	v_max3_f32 v95, v95, v83, v84
	v_max3_f32 v95, v95, v85, v86
	v_max3_f32 v95, v95, v87, v88
	v_max3_f32 v95, v95, v89, v90
	v_max3_f32 v95, v95, v91, v92
	v_max3_f32 v95, v95, v93, v94
	v_mov_b32_e32 v104, v95
	s_nop 1
	v_permlane32_swap_b32 v104, v95
	s_mov_b32 s22, 0x41000000
	s_waitcnt lgkmcnt(0)
	v_max_f32_e32 v95, v95, v104
	v_sub_f32_e32 v104, v95, v165
	v_cmp_lt_f32_e32 vcc, s22, v104
	s_nop 1
	v_cndmask_b32_e32 v106, v165, v95, vcc
	v_sub_f32_e32 v95, v165, v106
	v_exp_f32_e32 v95, v95
	s_nop 0
	v_cndmask_b32_e32 v104, 1.0, v95, vcc
	v_cmp_neq_f32_e32 vcc, 1.0, v104
	s_cbranch_vccz .LBB0_376
	v_pk_mul_f32 v[78:79], v[78:79], v[104:105] op_sel_hi:[1,0]
	v_pk_mul_f32 v[76:77], v[76:77], v[104:105] op_sel_hi:[1,0]
	v_pk_mul_f32 v[74:75], v[74:75], v[104:105] op_sel_hi:[1,0]
	v_pk_mul_f32 v[72:73], v[72:73], v[104:105] op_sel_hi:[1,0]
	v_pk_mul_f32 v[70:71], v[70:71], v[104:105] op_sel_hi:[1,0]
	v_pk_mul_f32 v[68:69], v[68:69], v[104:105] op_sel_hi:[1,0]
	v_pk_mul_f32 v[66:67], v[66:67], v[104:105] op_sel_hi:[1,0]
	v_pk_mul_f32 v[64:65], v[64:65], v[104:105] op_sel_hi:[1,0]
	v_pk_mul_f32 v[62:63], v[62:63], v[104:105] op_sel_hi:[1,0]
	v_pk_mul_f32 v[60:61], v[60:61], v[104:105] op_sel_hi:[1,0]
	v_pk_mul_f32 v[58:59], v[58:59], v[104:105] op_sel_hi:[1,0]
	v_pk_mul_f32 v[56:57], v[56:57], v[104:105] op_sel_hi:[1,0]
	v_pk_mul_f32 v[54:55], v[54:55], v[104:105] op_sel_hi:[1,0]
	v_pk_mul_f32 v[52:53], v[52:53], v[104:105] op_sel_hi:[1,0]
	v_pk_mul_f32 v[50:51], v[50:51], v[104:105] op_sel_hi:[1,0]
	v_pk_mul_f32 v[48:49], v[48:49], v[104:105] op_sel_hi:[1,0]
	v_pk_mul_f32 v[46:47], v[46:47], v[104:105] op_sel_hi:[1,0]
	v_pk_mul_f32 v[44:45], v[44:45], v[104:105] op_sel_hi:[1,0]
	v_pk_mul_f32 v[42:43], v[42:43], v[104:105] op_sel_hi:[1,0]
	v_pk_mul_f32 v[40:41], v[40:41], v[104:105] op_sel_hi:[1,0]
	v_pk_mul_f32 v[38:39], v[38:39], v[104:105] op_sel_hi:[1,0]
	v_pk_mul_f32 v[36:37], v[36:37], v[104:105] op_sel_hi:[1,0]
	v_pk_mul_f32 v[34:35], v[34:35], v[104:105] op_sel_hi:[1,0]
	v_pk_mul_f32 v[32:33], v[32:33], v[104:105] op_sel_hi:[1,0]
	v_pk_mul_f32 v[30:31], v[30:31], v[104:105] op_sel_hi:[1,0]
	v_pk_mul_f32 v[28:29], v[28:29], v[104:105] op_sel_hi:[1,0]
	v_pk_mul_f32 v[26:27], v[26:27], v[104:105] op_sel_hi:[1,0]
	v_pk_mul_f32 v[24:25], v[24:25], v[104:105] op_sel_hi:[1,0]
	v_pk_mul_f32 v[22:23], v[22:23], v[104:105] op_sel_hi:[1,0]
	v_pk_mul_f32 v[20:21], v[20:21], v[104:105] op_sel_hi:[1,0]
	v_pk_mul_f32 v[18:19], v[18:19], v[104:105] op_sel_hi:[1,0]
	v_pk_mul_f32 v[16:17], v[16:17], v[104:105] op_sel_hi:[1,0]

.LBB0_388:
	s_mul_i32 s13, s40, 0x4400
	v_add_u32_e32 v0, s13, v144
	ds_read_b128 v[2:5], v0
	ds_read_b128 v[6:9], v0 offset:32
	ds_read_b128 v[10:13], v0 offset:64
	ds_read_b128 v[162:165], v0 offset:96
	ds_read_b128 v[80:83], v0 offset:8704
	ds_read_b128 v[184:187], v0 offset:8736
	ds_read_b128 v[188:191], v0 offset:8768
	ds_read_b128 v[192:195], v0 offset:8800
	s_waitcnt lgkmcnt(0)
	s_add_i32 s68, s23, s22
	s_waitcnt lgkmcnt(7)
	v_mfma_f32_32x32x16_bf16 v[96:111], v[2:5], v[112:115], 0
	s_cmp_ge_u32 s67, s66
	s_cselect_b64 s[42:43], -1, 0
	s_cmp_lt_u32 s67, 2
	s_cselect_b64 s[44:45], -1, 0
	s_or_b64 s[42:43], s[44:45], s[42:43]
	s_andn2_b64 vcc, exec, s[42:43]
	s_waitcnt lgkmcnt(3)
	v_mfma_f32_32x32x16_bf16 v[80:95], v[80:83], v[112:115], 0
	v_mfma_f32_32x32x16_bf16 v[96:111], v[6:9], v[116:119], v[96:111]
	s_waitcnt lgkmcnt(2)
	v_mfma_f32_32x32x16_bf16 v[80:95], v[184:187], v[116:119], v[80:95]
	v_mfma_f32_32x32x16_bf16 v[96:111], v[10:13], v[120:123], v[96:111]
	s_waitcnt lgkmcnt(1)
	v_mfma_f32_32x32x16_bf16 v[80:95], v[188:191], v[120:123], v[80:95]
	v_mfma_f32_32x32x16_bf16 v[96:111], v[162:165], v[124:127], v[96:111]
	s_waitcnt lgkmcnt(0)
	v_mfma_f32_32x32x16_bf16 v[80:95], v[192:195], v[124:127], v[80:95]
	s_nop 9
	v_mul_f32_e64 v164, v98, s24
	v_mul_f32_e64 v165, v99, s24
	v_mul_f32_e64 v98, v100, s24
	v_mul_f32_e64 v99, v101, s24
	v_mul_f32_e64 v162, v96, s24
	v_mul_f32_e64 v163, v97, s24
	v_pk_mul_f32 v[96:97], v[102:103], s[24:25] op_sel_hi:[1,0]
	v_pk_mul_f32 v[12:13], v[104:105], s[24:25] op_sel_hi:[1,0]
	v_pk_mul_f32 v[8:9], v[106:107], s[24:25] op_sel_hi:[1,0]
	v_pk_mul_f32 v[4:5], v[108:109], s[24:25] op_sel_hi:[1,0]
	v_mul_f32_e32 v100, 0x3e38aa3b, v80
	v_pk_mul_f32 v[2:3], v[110:111], s[24:25] op_sel_hi:[1,0]
	v_mul_f32_e32 v6, 0x3e38aa3b, v81
	v_mul_f32_e32 v7, 0x3e38aa3b, v82
	v_mul_f32_e32 v10, 0x3e38aa3b, v83
	v_mul_f32_e32 v11, 0x3e38aa3b, v84
	v_mul_f32_e32 v14, 0x3e38aa3b, v85
	v_mul_f32_e32 v15, 0x3e38aa3b, v86
	v_mul_f32_e32 v80, 0x3e38aa3b, v87
	v_mul_f32_e32 v81, 0x3e38aa3b, v88
	v_mul_f32_e32 v82, 0x3e38aa3b, v89
	v_mul_f32_e32 v83, 0x3e38aa3b, v90
	v_mul_f32_e32 v84, 0x3e38aa3b, v91
	v_mul_f32_e32 v85, 0x3e38aa3b, v92
	v_mul_f32_e32 v86, 0x3e38aa3b, v93
	v_mul_f32_e32 v87, 0x3e38aa3b, v94
	v_mul_f32_e32 v88, 0x3e38aa3b, v95
	s_cbranch_vccnz .LBB0_390
	s_cmpk_lt_u32 s22, 0x80
	s_cbranch_scc1 .Lat_genmask_b
	v_add_u32_e32 v0, s22, v166
	v_sub_u32_e32 v0, v158, v0
	v_cmp_le_i32_e32 vcc, 0, v0
	v_cmp_le_i32_e64 s[42:43], 1, v0
	v_cmp_le_i32_e64 s[44:45], 2, v0
	v_cndmask_b32_e32 v162, v214, v162, vcc
	v_cmp_le_i32_e32 vcc, 3, v0
	v_cndmask_b32_e64 v163, v214, v163, s[42:43]
	v_cmp_le_i32_e64 s[42:43], 8, v0
	v_cndmask_b32_e64 v164, v214, v164, s[44:45]
	v_cmp_le_i32_e64 s[44:45], 9, v0
	v_cndmask_b32_e32 v165, v214, v165, vcc
	v_cmp_le_i32_e32 vcc, 10, v0
	v_cndmask_b32_e64 v98, v214, v98, s[42:43]
	v_cmp_le_i32_e64 s[42:43], 11, v0
	v_cndmask_b32_e64 v99, v214, v99, s[44:45]
	v_cmp_le_i32_e64 s[44:45], 16, v0
	v_cndmask_b32_e32 v96, v214, v96, vcc
	v_cmp_le_i32_e32 vcc, 17, v0
	v_cndmask_b32_e64 v97, v214, v97, s[42:43]
	v_cmp_le_i32_e64 s[42:43], 18, v0
	v_cndmask_b32_e64 v12, v214, v12, s[44:45]
	v_cmp_le_i32_e64 s[44:45], 19, v0
	v_cndmask_b32_e32 v13, v214, v13, vcc
	v_cmp_le_i32_e32 vcc, 24, v0
	v_cndmask_b32_e64 v8, v214, v8, s[42:43]
	v_cmp_le_i32_e64 s[42:43], 25, v0
	v_cndmask_b32_e64 v9, v214, v9, s[44:45]
	v_cmp_le_i32_e64 s[44:45], 26, v0
	v_cndmask_b32_e32 v4, v214, v4, vcc
	v_cmp_le_i32_e32 vcc, 27, v0
	v_cndmask_b32_e64 v5, v214, v5, s[42:43]
	v_cmp_le_i32_e64 s[42:43], 32, v0
	v_cndmask_b32_e64 v2, v214, v2, s[44:45]
	v_cmp_le_i32_e64 s[44:45], 33, v0
	v_cndmask_b32_e32 v3, v214, v3, vcc
	v_cmp_le_i32_e32 vcc, 34, v0
	v_cndmask_b32_e64 v100, v214, v100, s[42:43]
	v_cmp_le_i32_e64 s[42:43], 35, v0
	v_cndmask_b32_e64 v6, v214, v6, s[44:45]
	v_cmp_le_i32_e64 s[44:45], 40, v0
	v_cndmask_b32_e32 v7, v214, v7, vcc
	v_cmp_le_i32_e32 vcc, 41, v0
	v_cndmask_b32_e64 v10, v214, v10, s[42:43]
	v_cmp_le_i32_e64 s[42:43], 42, v0
	v_cndmask_b32_e64 v11, v214, v11, s[44:45]
	v_cmp_le_i32_e64 s[44:45], 43, v0
	v_cndmask_b32_e32 v14, v214, v14, vcc
	v_cmp_le_i32_e32 vcc, 48, v0
	v_cndmask_b32_e64 v15, v214, v15, s[42:43]
	v_cmp_le_i32_e64 s[42:43], 49, v0
	v_cndmask_b32_e64 v80, v214, v80, s[44:45]
	v_cmp_le_i32_e64 s[44:45], 50, v0
	v_cndmask_b32_e32 v81, v214, v81, vcc
	v_cmp_le_i32_e32 vcc, 51, v0
	v_cndmask_b32_e64 v82, v214, v82, s[42:43]
	v_cmp_le_i32_e64 s[42:43], 56, v0
	v_cndmask_b32_e64 v83, v214, v83, s[44:45]
	v_cmp_le_i32_e64 s[44:45], 57, v0
	v_cndmask_b32_e32 v84, v214, v84, vcc
	v_cmp_le_i32_e32 vcc, 58, v0
	v_cndmask_b32_e64 v85, v214, v85, s[42:43]
	v_cmp_le_i32_e64 s[42:43], 59, v0
	v_cndmask_b32_e64 v86, v214, v86, s[44:45]
	v_cndmask_b32_e32 v87, v214, v87, vcc
	v_cndmask_b32_e64 v88, v214, v88, s[42:43]
	s_branch .LBB0_390
.Lat_genmask_b:
	s_cmpk_gt_u32 s68, 0x6f
	v_add_u32_e32 v0, s22, v166
	s_cselect_b64 s[44:45], -1, 0
	v_cmp_eq_u32_e32 vcc, s22, v182
	s_or_b64 s[42:43], s[44:45], vcc
	v_cmp_le_u32_e32 vcc, v0, v158
	v_add_u32_e32 v89, s22, v175
	s_and_b64 vcc, vcc, s[42:43]
	v_cmp_eq_u32_e64 s[42:43], 0, v89
	v_cndmask_b32_e32 v162, v214, v162, vcc
	v_cmp_lt_u32_e32 vcc, v0, v158
	s_or_b64 s[42:43], s[44:45], s[42:43]
	v_add_u32_e32 v89, s22, v174
	s_and_b64 vcc, vcc, s[42:43]
	v_add_u32_e32 v90, 2, v0
	v_cmp_eq_u32_e64 s[42:43], 0, v89
	v_cndmask_b32_e32 v163, v214, v163, vcc
	v_cmp_le_u32_e32 vcc, v90, v158
	s_or_b64 s[42:43], s[44:45], s[42:43]
	v_add_u32_e32 v89, s22, v173
	s_and_b64 vcc, vcc, s[42:43]
	v_add_u32_e32 v90, 3, v0
	v_cmp_eq_u32_e64 s[42:43], 0, v89
	v_cndmask_b32_e32 v164, v214, v164, vcc
	v_cmp_le_u32_e32 vcc, v90, v158
	s_or_b64 s[42:43], s[44:45], s[42:43]
	v_add_u32_e32 v89, s22, v172
	s_and_b64 vcc, vcc, s[42:43]
	v_add_u32_e32 v90, 8, v0
	v_cmp_eq_u32_e64 s[42:43], 0, v89
	v_cndmask_b32_e32 v165, v214, v165, vcc
	v_cmp_le_u32_e32 vcc, v90, v158
	s_or_b64 s[42:43], s[44:45], s[42:43]
	v_add_u32_e32 v89, s22, v171
	s_and_b64 vcc, vcc, s[42:43]
	v_add_u32_e32 v90, 9, v0
	v_cmp_eq_u32_e64 s[42:43], 0, v89
	v_cndmask_b32_e32 v98, v214, v98, vcc
	v_cmp_le_u32_e32 vcc, v90, v158
	s_or_b64 s[42:43], s[44:45], s[42:43]
	v_add_u32_e32 v89, s22, v170
	s_and_b64 vcc, vcc, s[42:43]
	v_add_u32_e32 v90, 10, v0
	v_cmp_eq_u32_e64 s[42:43], 0, v89
	v_cndmask_b32_e32 v99, v214, v99, vcc
	v_cmp_le_u32_e32 vcc, v90, v158
	s_or_b64 s[42:43], s[44:45], s[42:43]
	v_add_u32_e32 v89, s22, v169
	s_and_b64 vcc, vcc, s[42:43]
	v_add_u32_e32 v90, 11, v0
	v_cmp_eq_u32_e64 s[42:43], 0, v89
	v_cndmask_b32_e32 v96, v214, v96, vcc
	v_cmp_le_u32_e32 vcc, v90, v158
	s_or_b64 s[42:43], s[44:45], s[42:43]
	v_or_b32_e32 v90, 16, v0
	s_and_b64 vcc, vcc, s[42:43]
	v_or_b32_e32 v89, 17, v0
	v_cmp_lt_u32_e64 s[48:49], s11, v90
	v_cmp_eq_u32_e64 s[52:53], v90, v158
	v_cndmask_b32_e32 v97, v214, v97, vcc
	v_cmp_le_u32_e32 vcc, v90, v158
	v_cmp_lt_u32_e64 s[44:45], s11, v89
	v_cmp_eq_u32_e64 s[50:51], v89, v145
	s_or_b64 s[48:49], s[48:49], s[52:53]
	v_cmp_le_u32_e64 s[42:43], v89, v145
	s_or_b64 s[44:45], s[44:45], s[50:51]
	s_and_b64 vcc, vcc, s[48:49]
	v_or_b32_e32 v90, 18, v0
	v_cndmask_b32_e32 v12, v214, v12, vcc
	s_and_b64 vcc, s[42:43], s[44:45]
	v_or_b32_e32 v89, 19, v0
	v_cmp_lt_u32_e64 s[48:49], s11, v90
	v_cmp_eq_u32_e64 s[52:53], v90, v158
	v_cndmask_b32_e32 v13, v214, v13, vcc
	v_cmp_le_u32_e32 vcc, v90, v158
	v_cmp_lt_u32_e64 s[44:45], s11, v89
	v_cmp_eq_u32_e64 s[50:51], v89, v145
	s_or_b64 s[48:49], s[48:49], s[52:53]
	v_cmp_le_u32_e64 s[42:43], v89, v145
	s_or_b64 s[44:45], s[44:45], s[50:51]
	s_and_b64 vcc, vcc, s[48:49]
	v_or_b32_e32 v90, 24, v0
	v_cndmask_b32_e32 v8, v214, v8, vcc
	s_and_b64 vcc, s[42:43], s[44:45]
	v_or_b32_e32 v89, 25, v0
	v_cmp_lt_u32_e64 s[48:49], s11, v90
	v_cmp_eq_u32_e64 s[52:53], v90, v158
	v_cndmask_b32_e32 v9, v214, v9, vcc
	v_cmp_le_u32_e32 vcc, v90, v158
	v_cmp_lt_u32_e64 s[44:45], s11, v89
	v_cmp_eq_u32_e64 s[50:51], v89, v145
	s_or_b64 s[48:49], s[48:49], s[52:53]
	v_cmp_le_u32_e64 s[42:43], v89, v145
	s_or_b64 s[44:45], s[44:45], s[50:51]
	s_and_b64 vcc, vcc, s[48:49]
	v_or_b32_e32 v90, 26, v0
	v_cndmask_b32_e32 v4, v214, v4, vcc
	s_and_b64 vcc, s[42:43], s[44:45]
	v_or_b32_e32 v89, 27, v0
	v_cmp_lt_u32_e64 s[48:49], s11, v90
	v_cmp_eq_u32_e64 s[52:53], v90, v158
	v_cndmask_b32_e32 v5, v214, v5, vcc
	v_cmp_le_u32_e32 vcc, v90, v158
	v_cmp_lt_u32_e64 s[44:45], s11, v89
	v_cmp_eq_u32_e64 s[50:51], v89, v145
	s_or_b64 s[48:49], s[48:49], s[52:53]
	v_cmp_le_u32_e64 s[42:43], v89, v145
	s_or_b64 s[44:45], s[44:45], s[50:51]
	s_and_b64 vcc, vcc, s[48:49]
	v_cndmask_b32_e32 v2, v214, v2, vcc
	s_and_b64 vcc, s[42:43], s[44:45]
	v_add_u32_e32 v89, s22, v168
	v_add_u32_e32 v90, 32, v0
	v_cndmask_b32_e32 v3, v214, v3, vcc
	v_cmp_lt_u32_e32 vcc, s11, v90
	v_cmp_eq_u32_e64 s[42:43], 0, v89
	s_or_b64 s[42:43], vcc, s[42:43]
	v_cmp_le_u32_e32 vcc, v90, v158
	v_or_b32_e32 v90, 33, v0
	s_and_b64 vcc, vcc, s[42:43]
	v_or_b32_e32 v89, 34, v0
	v_cmp_lt_u32_e64 s[48:49], s11, v90
	v_cmp_eq_u32_e64 s[52:53], v90, v158
	v_cndmask_b32_e32 v100, v214, v100, vcc
	v_cmp_le_u32_e32 vcc, v90, v158
	v_cmp_lt_u32_e64 s[44:45], s11, v89
	v_cmp_eq_u32_e64 s[50:51], v89, v145
	s_or_b64 s[48:49], s[48:49], s[52:53]
	v_cmp_le_u32_e64 s[42:43], v89, v145
	s_or_b64 s[44:45], s[44:45], s[50:51]
	s_and_b64 vcc, vcc, s[48:49]
	v_or_b32_e32 v90, 35, v0
	v_cndmask_b32_e32 v6, v214, v6, vcc
	s_and_b64 vcc, s[42:43], s[44:45]
	v_or_b32_e32 v89, 40, v0
	v_cmp_lt_u32_e64 s[48:49], s11, v90
	v_cmp_eq_u32_e64 s[52:53], v90, v158
	v_cndmask_b32_e32 v7, v214, v7, vcc
	v_cmp_le_u32_e32 vcc, v90, v158
	v_cmp_lt_u32_e64 s[44:45], s11, v89
	v_cmp_eq_u32_e64 s[50:51], v89, v145
	s_or_b64 s[48:49], s[48:49], s[52:53]
	v_cmp_le_u32_e64 s[42:43], v89, v145
	s_or_b64 s[44:45], s[44:45], s[50:51]
	s_and_b64 vcc, vcc, s[48:49]
	v_or_b32_e32 v90, 41, v0
	v_cndmask_b32_e32 v10, v214, v10, vcc
	s_and_b64 vcc, s[42:43], s[44:45]
	v_or_b32_e32 v89, 42, v0
	v_cmp_lt_u32_e64 s[48:49], s11, v90
	v_cmp_eq_u32_e64 s[52:53], v90, v158
	v_cndmask_b32_e32 v11, v214, v11, vcc
	v_cmp_le_u32_e32 vcc, v90, v158
	v_cmp_lt_u32_e64 s[44:45], s11, v89
	v_cmp_eq_u32_e64 s[50:51], v89, v145
	s_or_b64 s[48:49], s[48:49], s[52:53]
	v_cmp_le_u32_e64 s[42:43], v89, v145
	s_or_b64 s[44:45], s[44:45], s[50:51]
	s_and_b64 vcc, vcc, s[48:49]
	v_or_b32_e32 v90, 43, v0
	v_cndmask_b32_e32 v14, v214, v14, vcc
	s_and_b64 vcc, s[42:43], s[44:45]
	v_or_b32_e32 v89, 48, v0
	v_cmp_lt_u32_e64 s[48:49], s11, v90
	v_cmp_eq_u32_e64 s[52:53], v90, v158
	v_cndmask_b32_e32 v15, v214, v15, vcc
	v_cmp_le_u32_e32 vcc, v90, v158
	v_cmp_lt_u32_e64 s[44:45], s11, v89
	v_cmp_eq_u32_e64 s[50:51], v89, v145
	s_or_b64 s[48:49], s[48:49], s[52:53]
	v_cmp_le_u32_e64 s[42:43], v89, v145
	s_or_b64 s[44:45], s[44:45], s[50:51]
	s_and_b64 vcc, vcc, s[48:49]
	v_or_b32_e32 v90, 49, v0
	v_cndmask_b32_e32 v80, v214, v80, vcc
	s_and_b64 vcc, s[42:43], s[44:45]
	v_or_b32_e32 v89, 50, v0
	v_cmp_lt_u32_e64 s[48:49], s11, v90
	v_cmp_eq_u32_e64 s[52:53], v90, v158
	v_cndmask_b32_e32 v81, v214, v81, vcc
	v_cmp_le_u32_e32 vcc, v90, v158
	v_cmp_lt_u32_e64 s[44:45], s11, v89
	v_cmp_eq_u32_e64 s[50:51], v89, v145
	s_or_b64 s[48:49], s[48:49], s[52:53]
	v_cmp_le_u32_e64 s[42:43], v89, v145
	s_or_b64 s[44:45], s[44:45], s[50:51]
	s_and_b64 vcc, vcc, s[48:49]
	v_or_b32_e32 v90, 51, v0
	v_cndmask_b32_e32 v82, v214, v82, vcc
	s_and_b64 vcc, s[42:43], s[44:45]
	v_or_b32_e32 v89, 56, v0
	v_cmp_lt_u32_e64 s[48:49], s11, v90
	v_cmp_eq_u32_e64 s[52:53], v90, v158
	v_cndmask_b32_e32 v83, v214, v83, vcc
	v_cmp_le_u32_e32 vcc, v90, v158
	v_cmp_lt_u32_e64 s[44:45], s11, v89
	v_cmp_eq_u32_e64 s[50:51], v89, v145
	s_or_b64 s[48:49], s[48:49], s[52:53]
	v_cmp_le_u32_e64 s[42:43], v89, v145
	s_or_b64 s[44:45], s[44:45], s[50:51]
	s_and_b64 vcc, vcc, s[48:49]
	v_or_b32_e32 v90, 57, v0
	v_cndmask_b32_e32 v84, v214, v84, vcc
	s_and_b64 vcc, s[42:43], s[44:45]
	v_or_b32_e32 v89, 58, v0
	v_cmp_lt_u32_e64 s[48:49], s11, v90
	v_cmp_eq_u32_e64 s[52:53], v90, v158
	v_cndmask_b32_e32 v85, v214, v85, vcc
	v_cmp_le_u32_e32 vcc, v90, v158
	v_cmp_lt_u32_e64 s[44:45], s11, v89
	v_cmp_eq_u32_e64 s[50:51], v89, v145
	s_or_b64 s[48:49], s[48:49], s[52:53]
	v_cmp_le_u32_e64 s[42:43], v89, v145
	s_or_b64 s[44:45], s[44:45], s[50:51]
	s_and_b64 vcc, vcc, s[48:49]
	v_add_u32_e32 v89, s22, v167
	v_add_u32_e32 v0, 59, v0
	v_cndmask_b32_e32 v86, v214, v86, vcc
	s_and_b64 vcc, s[42:43], s[44:45]
	v_cmp_lt_u32_e64 s[42:43], s11, v0
	v_cmp_eq_u32_e64 s[44:45], 0, v89
	v_cndmask_b32_e32 v87, v214, v87, vcc
	v_cmp_le_u32_e32 vcc, v0, v158
	s_or_b64 s[42:43], s[42:43], s[44:45]
	s_and_b64 vcc, vcc, s[42:43]
	v_cndmask_b32_e32 v88, v214, v88, vcc
.LBB0_390:
	s_mov_b32 s13, 0xff800000
	v_max3_f32 v0, v162, s13, v163
	v_max3_f32 v0, v0, v164, v165
	v_max3_f32 v0, v0, v98, v99
	v_max3_f32 v0, v0, v96, v97
	v_max3_f32 v0, v0, v12, v13
	v_max3_f32 v0, v0, v8, v9
	v_max3_f32 v0, v0, v4, v5
	v_max3_f32 v0, v0, v2, v3
	v_max3_f32 v0, v0, v100, v6
	v_max3_f32 v0, v0, v7, v10
	v_max3_f32 v0, v0, v11, v14
	v_max3_f32 v0, v0, v15, v80
	v_max3_f32 v0, v0, v81, v82
	v_max3_f32 v0, v0, v83, v84
	v_max3_f32 v0, v0, v85, v86
	v_max3_f32 v0, v0, v87, v88
	v_mov_b32_e32 v89, v0
	s_nop 1
	v_permlane32_swap_b32 v89, v0
	s_mov_b32 s13, 0x41000000
	s_waitcnt lgkmcnt(0)
	v_max_f32_e32 v0, v0, v89
	v_sub_f32_e32 v89, v0, v152
	v_cmp_lt_f32_e32 vcc, s13, v89
	s_nop 1
	v_cndmask_b32_e32 v89, v152, v0, vcc
	v_sub_f32_e32 v0, v152, v89
	v_exp_f32_e32 v0, v0
	s_nop 0
	v_cndmask_b32_e32 v0, 1.0, v0, vcc
	v_cmp_neq_f32_e32 vcc, 1.0, v0
	s_cbranch_vccz .LBB0_392
	v_pk_mul_f32 v[78:79], v[78:79], v[0:1] op_sel_hi:[1,0]
	v_pk_mul_f32 v[76:77], v[76:77], v[0:1] op_sel_hi:[1,0]
	v_pk_mul_f32 v[74:75], v[74:75], v[0:1] op_sel_hi:[1,0]
	v_pk_mul_f32 v[72:73], v[72:73], v[0:1] op_sel_hi:[1,0]
	v_pk_mul_f32 v[70:71], v[70:71], v[0:1] op_sel_hi:[1,0]
	v_pk_mul_f32 v[68:69], v[68:69], v[0:1] op_sel_hi:[1,0]
	v_pk_mul_f32 v[66:67], v[66:67], v[0:1] op_sel_hi:[1,0]
	v_pk_mul_f32 v[64:65], v[64:65], v[0:1] op_sel_hi:[1,0]
	v_pk_mul_f32 v[62:63], v[62:63], v[0:1] op_sel_hi:[1,0]
	v_pk_mul_f32 v[60:61], v[60:61], v[0:1] op_sel_hi:[1,0]
	v_pk_mul_f32 v[58:59], v[58:59], v[0:1] op_sel_hi:[1,0]
	v_pk_mul_f32 v[56:57], v[56:57], v[0:1] op_sel_hi:[1,0]
	v_pk_mul_f32 v[54:55], v[54:55], v[0:1] op_sel_hi:[1,0]
	v_pk_mul_f32 v[52:53], v[52:53], v[0:1] op_sel_hi:[1,0]
	v_pk_mul_f32 v[50:51], v[50:51], v[0:1] op_sel_hi:[1,0]
	v_pk_mul_f32 v[48:49], v[48:49], v[0:1] op_sel_hi:[1,0]
	v_pk_mul_f32 v[46:47], v[46:47], v[0:1] op_sel_hi:[1,0]
	v_pk_mul_f32 v[44:45], v[44:45], v[0:1] op_sel_hi:[1,0]
	v_pk_mul_f32 v[42:43], v[42:43], v[0:1] op_sel_hi:[1,0]
	v_pk_mul_f32 v[40:41], v[40:41], v[0:1] op_sel_hi:[1,0]
	v_pk_mul_f32 v[38:39], v[38:39], v[0:1] op_sel_hi:[1,0]
	v_pk_mul_f32 v[36:37], v[36:37], v[0:1] op_sel_hi:[1,0]
	v_pk_mul_f32 v[34:35], v[34:35], v[0:1] op_sel_hi:[1,0]
	v_pk_mul_f32 v[32:33], v[32:33], v[0:1] op_sel_hi:[1,0]
	v_pk_mul_f32 v[30:31], v[30:31], v[0:1] op_sel_hi:[1,0]
	v_pk_mul_f32 v[28:29], v[28:29], v[0:1] op_sel_hi:[1,0]
	v_pk_mul_f32 v[26:27], v[26:27], v[0:1] op_sel_hi:[1,0]
	v_pk_mul_f32 v[24:25], v[24:25], v[0:1] op_sel_hi:[1,0]
	v_pk_mul_f32 v[22:23], v[22:23], v[0:1] op_sel_hi:[1,0]
	v_pk_mul_f32 v[20:21], v[20:21], v[0:1] op_sel_hi:[1,0]
	v_pk_mul_f32 v[18:19], v[18:19], v[0:1] op_sel_hi:[1,0]
	v_pk_mul_f32 v[16:17], v[16:17], v[0:1] op_sel_hi:[1,0]
